# v039_attnepi
# speedup vs baseline: 1.0387x; 1.0173x over previous
; __device__ __forceinline__ void attn_wave_item(const Params& p, int witem, const int tidx) {
;     ...
;   u16* yo = yraw + (size_t)(b * SEQ + t0 + n) * DM + 1024 + h * 128;
; #pragma unroll
;   for (int dt = 0; dt < 4; ++dt)
; #pragma unroll
;     for (int rg = 0; rg < 4; ++rg) {
;       u32x2 o = {pack2(O[dt][rg * 4 + 0], O[dt][rg * 4 + 1]), pack2(O[dt][rg * 4 + 2], O[dt][rg * 4 + 3])};
;       *reinterpret_cast<u32x2*>(yo + dt * 32 + 8 * rg + 4 * half) = o;
;     }
.LBB0_121:
	s_or_b64 exec, exec, s[88:89]
	s_and_saveexec_b64 s[6:7], s[56:57]
	s_xor_b64 s[6:7], exec, s[6:7]
	s_or_b64 exec, exec, s[6:7]
	v_lshlrev_b64 v[64:65], 13, v[166:167]
	v_lshl_add_u64 v[64:65], s[86:87], 0, v[64:65]
	v_lshlrev_b32_e32 v162, 1, v168
	v_lshl_add_u64 v[64:65], v[64:65], 0, v[162:163]
	v_lshlrev_b32_e32 v162, 1, v165
	v_lshl_add_u64 v[64:65], v[64:65], 0, v[162:163]
	s_mov_b64 s[6:7], 0x22900800
	v_lshl_add_u64 v[66:67], v[64:65], 0, s[6:7]
	v_lshrrev_b32_e32 v64, 5, v215
	v_lshlrev_b32_e32 v64, 3, v64
	v_add_co_u32_e32 v66, vcc, v66, v64
	s_nop 1
	v_addc_co_u32_e32 v67, vcc, 0, v67, vcc
	v_cvt_pk_bf16_f32 v48, v48, v49
	v_cvt_pk_bf16_f32 v49, v50, v51
	v_cvt_pk_bf16_f32 v50, v52, v53
	v_cvt_pk_bf16_f32 v51, v54, v55
	v_cvt_pk_bf16_f32 v56, v56, v57
	v_cvt_pk_bf16_f32 v57, v58, v59
	v_cvt_pk_bf16_f32 v58, v60, v61
	v_cvt_pk_bf16_f32 v59, v62, v63
	v_cvt_pk_bf16_f32 v32, v32, v33
	v_cvt_pk_bf16_f32 v33, v34, v35
	v_cvt_pk_bf16_f32 v34, v36, v37
	v_cvt_pk_bf16_f32 v35, v38, v39
	v_cvt_pk_bf16_f32 v40, v40, v41
	v_cvt_pk_bf16_f32 v41, v42, v43
	v_cvt_pk_bf16_f32 v42, v44, v45
	v_cvt_pk_bf16_f32 v43, v46, v47
	v_cvt_pk_bf16_f32 v16, v16, v17
	v_cvt_pk_bf16_f32 v17, v18, v19
	v_cvt_pk_bf16_f32 v18, v20, v21
	v_cvt_pk_bf16_f32 v19, v22, v23
	v_cvt_pk_bf16_f32 v24, v24, v25
	v_cvt_pk_bf16_f32 v25, v26, v27
	v_cvt_pk_bf16_f32 v26, v28, v29
	v_cvt_pk_bf16_f32 v27, v30, v31
	v_cvt_pk_bf16_f32 v0, v0, v1
	v_cvt_pk_bf16_f32 v1, v2, v3
	v_cvt_pk_bf16_f32 v2, v4, v5
	v_cvt_pk_bf16_f32 v3, v6, v7
	v_cvt_pk_bf16_f32 v8, v8, v9
	v_cvt_pk_bf16_f32 v9, v10, v11
	v_cvt_pk_bf16_f32 v10, v12, v13
	v_cvt_pk_bf16_f32 v11, v14, v15
	s_nop 1
	v_permlane32_swap_b32 v48, v50
	v_permlane32_swap_b32 v49, v51
	v_permlane32_swap_b32 v56, v58
	v_permlane32_swap_b32 v57, v59
	v_permlane32_swap_b32 v32, v34
	v_permlane32_swap_b32 v33, v35
	v_permlane32_swap_b32 v40, v42
	v_permlane32_swap_b32 v41, v43
	v_permlane32_swap_b32 v16, v18
	v_permlane32_swap_b32 v17, v19
	v_permlane32_swap_b32 v24, v26
	v_permlane32_swap_b32 v25, v27
	v_permlane32_swap_b32 v0, v2
	v_permlane32_swap_b32 v1, v3
	v_permlane32_swap_b32 v8, v10
	v_permlane32_swap_b32 v9, v11
	global_store_dwordx4 v[66:67], v[48:51], off
	global_store_dwordx4 v[66:67], v[56:59], off offset:32
	global_store_dwordx4 v[66:67], v[32:35], off offset:64
	global_store_dwordx4 v[66:67], v[40:43], off offset:96
	global_store_dwordx4 v[66:67], v[16:19], off offset:128
	global_store_dwordx4 v[66:67], v[24:27], off offset:160
	global_store_dwordx4 v[66:67], v[0:3], off offset:192
	global_store_dwordx4 v[66:67], v[8:11], off offset:224
	v_readlane_b32 s8, v255, 39
	v_readlane_b32 s88, v254, 31
	v_readlane_b32 s9, v255, 40
	v_readlane_b32 s42, v254, 27
	v_readlane_b32 s48, v254, 29
	v_readlane_b32 s89, v254, 32
	s_mov_b64 s[44:45], s[8:9]
	v_readlane_b32 s43, v254, 28
	v_readlane_b32 s49, v254, 30
	s_movk_i32 s50, 0x100
	s_movk_i32 s51, 0x2000
	s_movk_i32 s56, 0x1000
	v_readlane_b32 s10, v255, 41
	v_readlane_b32 s11, v255, 42
